# diff_attn tail steps: PV half-1 V-fragment LDS reads batched into free quads with counted lgkmcnt (stacked on v10)
# baseline (speedup 1.0000x reference)
; DI float fexp2(float x) { return __builtin_amdgcn_exp2f(x); }
; DI void diff_attn_phase(int wv, LAS unsigned char* lds, const bf16_t* qk, const bf16_t* vt, bf16_t* ob, const float* lq1, const float* lk1, const float* lq2, const float* lk2,
;                         const float* subg, int layer_idx) {
;     ...
;                 float mx = -INFINITY, mx1 = -INFINITY;
; #pragma unroll
;                 for (int i = 0; i < 16; ++i) { mx = fmaxf(mx, S0[i]); mx1 = fmaxf(mx1, S1[i]); }
;                 mx = fmaxf(mx, mx1 + b32) + base;
;                 mx = fmaxf(mx, __shfl_xor(mx, 32));
;                 {
;                     const float mn = fmaxf(m, mx), alpha = fexp2(m - mn); m = mn; l *= alpha;
; #pragma unroll
;                     for (int d = 0; d < 4; ++d) O[d] = O[d] * alpha;
.LBB0_430:
	v_max_f32_e32 v76, v206, v206
	v_max3_f32 v77, v202, s54, v203
	v_max_f32_e32 v76, 0xff800000, v76
	v_max3_f32 v77, v77, v198, v199
	v_max3_f32 v76, v76, v207, v204
	v_max3_f32 v77, v77, v194, v195
	v_max3_f32 v76, v76, v205, v200
	v_max3_f32 v77, v77, v86, v87
	v_max3_f32 v76, v76, v201, v196
	v_max3_f32 v77, v77, v82, v83
	v_sub_u32_e32 v0, v0, v162
	v_max3_f32 v76, v76, v197, v88
	v_max3_f32 v77, v77, v70, v71
	v_cvt_f32_i32_e32 v0, v0
	v_max3_f32 v76, v76, v89, v84
	v_max3_f32 v77, v77, v66, v67
	v_max3_f32 v76, v76, v85, v72
	v_max3_f32 v77, v77, v74, v75
	v_max3_f32 v76, v76, v73, v68
	v_add_f32_e32 v77, v157, v77
	v_max3_f32 v76, v76, v69, v77
	v_fmac_f32_e32 v76, v160, v0
	v_mov_b32_e32 v77, v76
	s_nop 1
	v_permlane32_swap_b32_e32 v76, v77
	s_waitcnt lgkmcnt(0)
	v_max3_f32 v77, v218, v76, v77
	v_fma_f32 v78, v160, v0, -v77
	v_add_f32_e32 v79, v157, v78
	v_add_f32_e32 v86, v86, v79
	v_add_f32_e32 v88, v88, v78
	v_add_f32_e32 v87, v87, v79
	v_add_f32_e32 v70, v70, v79
	v_add_f32_e32 v0, v206, v78
	v_add_f32_e32 v94, v200, v78
	v_exp_f32_e32 v206, v86
	v_add_f32_e32 v86, v195, v79
	v_exp_f32_e32 v195, v88
	v_exp_f32_e32 v88, v87
	v_add_f32_e32 v87, v89, v78
	v_exp_f32_e32 v89, v70
	v_add_f32_e32 v70, v83, v79
	v_add_f32_e32 v66, v66, v79
	v_add_f32_e32 v90, v204, v78
	v_exp_f32_e32 v193, v94
	v_add_f32_e32 v94, v194, v79
	v_exp_f32_e32 v194, v70
	v_add_f32_e32 v70, v85, v78
	v_exp_f32_e32 v85, v66
	v_add_f32_e32 v66, v71, v79
	v_exp_f32_e32 v95, v90
	v_add_f32_e32 v90, v198, v79
	v_exp_f32_e32 v198, v66
	v_add_f32_e32 v66, v73, v78
	v_exp_f32_e32 v80, v0
	v_add_f32_e32 v0, v202, v79
	v_add_f32_e32 v68, v68, v78
	v_exp_f32_e32 v200, v66
	v_add_f32_e32 v66, v67, v79
	v_sub_f32_e32 v76, v218, v77
	v_exp_f32_e32 v81, v0
	v_add_f32_e32 v0, v207, v78
	v_add_f32_e32 v168, v196, v78
	v_exp_f32_e32 v73, v68
	v_add_f32_e32 v68, v74, v79
	v_exp_f32_e32 v74, v66
	v_add_f32_e32 v66, v69, v78
	v_exp_f32_e32 v76, v76
	v_exp_f32_e32 v191, v90
	v_exp_f32_e32 v90, v0
	v_add_f32_e32 v0, v203, v79
	v_add_f32_e32 v92, v205, v78
	v_exp_f32_e32 v205, v94
	v_add_f32_e32 v94, v199, v79
	v_add_f32_e32 v96, v201, v78
	v_exp_f32_e32 v199, v168
	v_add_f32_e32 v168, v197, v78
	v_add_f32_e32 v82, v82, v79
	v_add_f32_e32 v84, v84, v78
	v_add_f32_e32 v72, v72, v78
	v_exp_f32_e32 v202, v66
	v_add_f32_e32 v66, v75, v79
	v_exp_f32_e32 v0, v0
	v_exp_f32_e32 v92, v92
	v_exp_f32_e32 v94, v94
	v_exp_f32_e32 v96, v96
	v_exp_f32_e32 v86, v86
	v_exp_f32_e32 v82, v82
	v_exp_f32_e32 v168, v168
	v_exp_f32_e32 v84, v84
	v_exp_f32_e32 v170, v87
	v_exp_f32_e32 v72, v72
	v_exp_f32_e32 v196, v70
	v_exp_f32_e32 v87, v68
	v_exp_f32_e32 v204, v66
	v_pk_mul_f32 v[64:65], v[64:65], v[76:77] op_sel_hi:[1,0]
	v_pk_mul_f32 v[62:63], v[62:63], v[76:77] op_sel_hi:[1,0]
	v_pk_mul_f32 v[60:61], v[60:61], v[76:77] op_sel_hi:[1,0]
	v_pk_mul_f32 v[58:59], v[58:59], v[76:77] op_sel_hi:[1,0]
	v_pk_mul_f32 v[56:57], v[56:57], v[76:77] op_sel_hi:[1,0]
	v_pk_mul_f32 v[54:55], v[54:55], v[76:77] op_sel_hi:[1,0]
	v_pk_mul_f32 v[52:53], v[52:53], v[76:77] op_sel_hi:[1,0]
	v_pk_mul_f32 v[50:51], v[50:51], v[76:77] op_sel_hi:[1,0]
	v_pk_mul_f32 v[48:49], v[48:49], v[76:77] op_sel_hi:[1,0]
	v_pk_mul_f32 v[46:47], v[46:47], v[76:77] op_sel_hi:[1,0]
	v_pk_mul_f32 v[44:45], v[44:45], v[76:77] op_sel_hi:[1,0]
	v_pk_mul_f32 v[42:43], v[42:43], v[76:77] op_sel_hi:[1,0]
	v_pk_mul_f32 v[40:41], v[40:41], v[76:77] op_sel_hi:[1,0]
	v_pk_mul_f32 v[38:39], v[38:39], v[76:77] op_sel_hi:[1,0]
	v_pk_mul_f32 v[36:37], v[36:37], v[76:77] op_sel_hi:[1,0]
	v_pk_mul_f32 v[34:35], v[34:35], v[76:77] op_sel_hi:[1,0]
	v_pk_mul_f32 v[32:33], v[32:33], v[76:77] op_sel_hi:[1,0]
	v_pk_mul_f32 v[30:31], v[30:31], v[76:77] op_sel_hi:[1,0]
	v_pk_mul_f32 v[28:29], v[28:29], v[76:77] op_sel_hi:[1,0]
	v_pk_mul_f32 v[26:27], v[26:27], v[76:77] op_sel_hi:[1,0]
	v_pk_mul_f32 v[24:25], v[24:25], v[76:77] op_sel_hi:[1,0]
	v_pk_mul_f32 v[22:23], v[22:23], v[76:77] op_sel_hi:[1,0]
	v_pk_mul_f32 v[20:21], v[20:21], v[76:77] op_sel_hi:[1,0]
; #define LAS __attribute__((address_space(3)))
; #define MFMA32(a, b, c) __builtin_amdgcn_mfma_f32_32x32x16_bf16((a), (b), (c), 0, 0, 0)
; DI void diff_attn_phase(int wv, LAS unsigned char* lds, const bf16_t* qk, const bf16_t* vt, bf16_t* ob, const float* lq1, const float* lk1, const float* lq2, const float* lk2,
;                         const float* subg, int layer_idx) {
;     ...
;                 l += ps;
;                 const bf16x8 p0 = pack8(S0, 0), p1 = pack8(S0, 1), p2 = pack8(S1, 0), p3 = pack8(S1, 1);
;                 __builtin_amdgcn_sched_barrier(0);
; #pragma unroll
;                 for (int d = 0; d < 4; ++d) { O[d] = MFMA32(vf[d][0], p0, O[d]); O[d] = MFMA32(vf[d][1], p1, O[d]); }
;                 __builtin_amdgcn_sched_barrier(0);
; #pragma unroll
;                 for (int d = 0; d < 4; ++d)
; #pragma unroll
;                     for (int s2 = 0; s2 < 2; ++s2) vf[d][s2] = *(const LAS bf16x8*)(buf + voff + d * 32 * DA_VP + (32 + 16 * s2) * 2);
; #pragma unroll
;                 for (int d = 0; d < 4; ++d) { O[d] = MFMA32(vf[d][0], p2, O[d]); O[d] = MFMA32(vf[d][1], p3, O[d]); }
	v_pk_mul_f32 v[18:19], v[18:19], v[76:77] op_sel_hi:[1,0]
	v_pk_mul_f32 v[16:17], v[16:17], v[76:77] op_sel_hi:[1,0]
	v_pk_mul_f32 v[14:15], v[14:15], v[76:77] op_sel_hi:[1,0]
	v_pk_mul_f32 v[12:13], v[12:13], v[76:77] op_sel_hi:[1,0]
	v_pk_mul_f32 v[10:11], v[10:11], v[76:77] op_sel_hi:[1,0]
	v_pk_mul_f32 v[8:9], v[8:9], v[76:77] op_sel_hi:[1,0]
	v_pk_mul_f32 v[6:7], v[6:7], v[76:77] op_sel_hi:[1,0]
	v_pk_mul_f32 v[4:5], v[4:5], v[76:77] op_sel_hi:[1,0]
	v_pk_mul_f32 v[2:3], v[2:3], v[76:77] op_sel_hi:[1,0]
	v_add_f32_e32 v91, v80, v81
	v_add_f32_e32 v93, v95, v191
	v_add_f32_e32 v97, v193, v205
	v_add_f32_e32 v169, v199, v206
	v_add_f32_e32 v171, v195, v82
	v_add_f32_e32 v197, v84, v89
	v_add_f32_e32 v201, v72, v85
	v_add_f32_e32 v203, v73, v87
	v_cvt_pk_bf16_f32 v66, v80, v90
	v_cvt_pk_bf16_f32 v67, v95, v92
	v_cvt_pk_bf16_f32 v68, v193, v96
	v_cvt_pk_bf16_f32 v69, v199, v168
	v_cvt_pk_bf16_f32 v70, v195, v170
	v_cvt_pk_bf16_f32 v71, v84, v196
	v_cvt_pk_bf16_f32 v72, v72, v200
	v_cvt_pk_bf16_f32 v73, v73, v202
	v_cvt_pk_bf16_f32 v78, v81, v0
	v_cvt_pk_bf16_f32 v79, v191, v94
	v_cvt_pk_bf16_f32 v80, v205, v86
	v_cvt_pk_bf16_f32 v81, v206, v88
	v_cvt_pk_bf16_f32 v82, v82, v194
	v_cvt_pk_bf16_f32 v83, v89, v198
	v_cvt_pk_bf16_f32 v84, v85, v74
	v_cvt_pk_bf16_f32 v85, v87, v204
	v_pk_add_f32 v[90:91], v[90:91], v[0:1]
	v_mfma_f32_32x32x16_bf16 v[50:65], v[142:145], v[66:69], v[50:65]
	v_pk_add_f32 v[90:91], v[90:91], v[90:91] op_sel_hi:[0,1]
	v_mov_b32_e32 v95, v91
	v_pk_add_f32 v[90:91], v[92:93], v[94:95]
	s_nop 0
	v_pk_add_f32 v[90:91], v[90:91], v[90:91] op_sel_hi:[0,1]
	v_mov_b32_e32 v87, v91
	v_pk_add_f32 v[86:87], v[96:97], v[86:87]
	v_mfma_f32_32x32x16_bf16 v[34:49], v[134:137], v[66:69], v[34:49]
	v_pk_add_f32 v[86:87], v[86:87], v[86:87] op_sel_hi:[0,1]
	v_mov_b32_e32 v89, v87
	v_pk_add_f32 v[86:87], v[168:169], v[88:89]
	s_nop 0
	v_pk_add_f32 v[86:87], v[86:87], v[86:87] op_sel_hi:[0,1]
	v_mov_b32_e32 v195, v87
	v_pk_add_f32 v[86:87], v[170:171], v[194:195]
	v_mfma_f32_32x32x16_bf16 v[18:33], v[126:129], v[66:69], v[18:33]
	v_pk_add_f32 v[86:87], v[86:87], v[86:87] op_sel_hi:[0,1]
	v_mov_b32_e32 v199, v87
	v_mfma_f32_32x32x16_bf16 v[2:17], v[118:121], v[66:69], v[2:17]
	v_add_f32_e64 v66, v196, v198
	v_add_f32_e64 v67, v197, v199
	v_pk_add_f32 v[66:67], v[66:67], v[66:67] op_sel_hi:[0,1]
	v_mov_b32_e32 v75, v67
	v_pk_add_f32 v[66:67], v[200:201], v[74:75]
	s_nop 0
	v_pk_add_f32 v[66:67], v[66:67], v[66:67] op_sel_hi:[0,1]
	v_mfma_f32_32x32x16_bf16 v[50:65], v[138:141], v[70:73], v[50:65]
	v_mov_b32_e32 v205, v67
	v_add_f32_e64 v66, v202, v204
	v_add_f32_e64 v67, v203, v205
	v_add_f32_e32 v0, v66, v67
	v_mfma_f32_32x32x16_bf16 v[34:49], v[130:133], v[70:73], v[34:49]
	v_mfma_f32_32x32x16_bf16 v[18:33], v[122:125], v[70:73], v[18:33]
	v_mfma_f32_32x32x16_bf16 v[2:17], v[114:117], v[70:73], v[2:17]
	ds_read_b128 v[66:69], v212 offset:17472
	ds_read_b128 v[114:117], v212 offset:17504
	ds_read_b128 v[118:121], v212 offset:22080
	ds_read_b128 v[122:125], v212 offset:22112
	ds_read_b128 v[126:129], v212 offset:26688
	ds_read_b128 v[130:133], v212 offset:26720
	ds_read_b128 v[134:137], v212 offset:31296
	ds_read_b128 v[138:141], v212 offset:31328
	v_fmac_f32_e32 v0, v159, v76
	v_mov_b32_e32 v218, v77
	v_mov_b32_e32 v159, v0
	s_waitcnt lgkmcnt(7)
	v_mfma_f32_32x32x16_bf16 v[50:65], v[66:69], v[78:81], v[50:65]
	s_waitcnt lgkmcnt(6)
	v_mfma_f32_32x32x16_bf16 v[50:65], v[114:117], v[82:85], v[50:65]
	s_waitcnt lgkmcnt(5)
	v_mfma_f32_32x32x16_bf16 v[34:49], v[118:121], v[78:81], v[34:49]
	s_waitcnt lgkmcnt(4)
	v_mfma_f32_32x32x16_bf16 v[34:49], v[122:125], v[82:85], v[34:49]
	s_waitcnt lgkmcnt(3)
	v_mfma_f32_32x32x16_bf16 v[18:33], v[126:129], v[78:81], v[18:33]
	s_waitcnt lgkmcnt(2)
	v_mfma_f32_32x32x16_bf16 v[18:33], v[130:133], v[82:85], v[18:33]
	s_waitcnt lgkmcnt(1)
	v_mfma_f32_32x32x16_bf16 v[2:17], v[134:137], v[78:81], v[2:17]
	s_waitcnt lgkmcnt(0)
	v_mfma_f32_32x32x16_bf16 v[2:17], v[138:141], v[82:85], v[2:17]

; #define LAS __attribute__((address_space(3)))
; #define MFMA32(a, b, c) __builtin_amdgcn_mfma_f32_32x32x16_bf16((a), (b), (c), 0, 0, 0)
; DI f32x16 zero16() { f32x16 z; for (int i = 0; i < 16; ++i) z[i] = 0.f; return z; }
; DI void diff_attn_phase(int wv, LAS unsigned char* lds, const bf16_t* qk, const bf16_t* vt, bf16_t* ob, const float* lq1, const float* lk1, const float* lq2, const float* lk2,
;                         const float* subg, int layer_idx) {
;     ...
;             if (key0 <= q0 + 31) {
;                 f32x16 S0 = zero16(), S1 = zero16();
;                 {
;                     bf16x8 kf[2][4];
; #pragma unroll
;                     for (int sub = 0; sub < 2; ++sub)
; #pragma unroll
;                         for (int ks = 0; ks < 4; ++ks) kf[sub][ks] = *(const LAS bf16x8*)(buf + koff + sub * 32 * DA_KP + ks * 32);
; #pragma unroll
;                     for (int ks = 0; ks < 4; ++ks) { const bf16x8 qfr = *(const LAS bf16x8*)(qlds + ks * 1024); S0 = MFMA32(kf[0][ks], qfr, S0); S1 = MFMA32(kf[1][ks], qfr, S1); }
;                 }
;                 __builtin_amdgcn_sched_barrier(0);
;                 bf16x8 vf[4][2];
; #pragma unroll
;                 for (int d = 0; d < 4; ++d)
; #pragma unroll
;                     for (int s2 = 0; s2 < 2; ++s2) vf[d][s2] = *(const LAS bf16x8*)(buf + voff + d * 32 * DA_VP + (16 * s2) * 2);
;                 const float base = slope2 * (float)(key0 + 8 * hh - qpos), b32 = 32.f * slope2;
; #pragma unroll
;                 for (int i = 0; i < 16; ++i) { S0[i] = S0[i] * c1 + cb[i]; S1[i] = S1[i] * c1 + cb[i]; }
;                 if (key0 + 63 > q0) {
;                     const int kq = qpos - key0 - 8 * hh;
; #pragma unroll
;                     for (int i = 0; i < 16; ++i) { const int ko = (i & 7) + 16 * (i >> 3); S0[i] = (ko > kq) ? -INFINITY : S0[i]; S1[i] = (ko + 32 > kq) ? -INFINITY : S1[i]; }
;                 }
;                 float mx = -INFINITY, mx1 = -INFINITY;
; #pragma unroll
;                 for (int i = 0; i < 16; ++i) { mx = fmaxf(mx, S0[i]); mx1 = fmaxf(mx1, S1[i]); }
;                 mx = fmaxf(mx, mx1 + b32) + base;
;                 mx = fmaxf(mx, __shfl_xor(mx, 32));
.LBB0_433:
	s_cmp_gt_i32 s16, s1
	s_cbranch_scc1 .LBB0_435
	ds_read_b128 v[66:69], v219 offset:35840
	ds_read_b128 v[114:117], v219 offset:35872
	ds_read_b128 v[118:121], v219 offset:35904
	ds_read_b128 v[122:125], v219 offset:35936
	ds_read_b128 v[82:85], v219 offset:44544
	ds_read_b128 v[126:129], v219 offset:44576
	ds_read_b128 v[130:133], v219 offset:44608
	ds_read_b128 v[134:137], v219 offset:44640
	ds_read_b128 v[86:89], v217
	ds_read_b128 v[138:141], v217 offset:1024
	ds_read_b128 v[142:145], v217 offset:2048
	ds_read_b128 v[194:197], v217 offset:3072
	s_waitcnt lgkmcnt(3)
	v_mfma_f32_32x32x16_bf16 v[66:81], v[66:69], v[86:89], 0
	v_or_b32_e32 v0, s16, v146
	v_mfma_f32_32x32x16_bf16 v[82:97], v[82:85], v[86:89], 0
	s_waitcnt lgkmcnt(2)
	v_mfma_f32_32x32x16_bf16 v[82:97], v[126:129], v[138:141], v[82:97]
	v_sub_u32_e32 v126, v0, v162
	v_sub_u32_e32 v0, v162, v0
	v_cmp_lt_i32_e32 vcc, -1, v0
	v_cvt_f32_i32_e32 v126, v126
	v_mfma_f32_32x32x16_bf16 v[66:81], v[114:117], v[138:141], v[66:81]
	s_waitcnt lgkmcnt(1)
	v_mfma_f32_32x32x16_bf16 v[82:97], v[130:133], v[142:145], v[82:97]
	v_mfma_f32_32x32x16_bf16 v[66:81], v[118:121], v[142:145], v[66:81]
	s_waitcnt lgkmcnt(0)
	v_mfma_f32_32x32x16_bf16 v[82:97], v[134:137], v[194:197], v[82:97]
	v_mfma_f32_32x32x16_bf16 v[66:81], v[122:125], v[194:197], v[66:81]
	s_nop 10
	v_fmamk_f32 v82, v82, 0x3e38aa3b, v192
	v_fmamk_f32 v83, v83, 0x3e38aa3b, v160
	v_fmamk_f32 v84, v84, 0x3e38aa3b, v188
	v_fmamk_f32 v85, v85, 0x3e38aa3b, v189
	v_fmamk_f32 v86, v86, 0x3e38aa3b, v186
	v_fmamk_f32 v87, v87, 0x3e38aa3b, v187
	v_fmamk_f32 v88, v88, 0x3e38aa3b, v184
	v_fmac_f32_e32 v192, 0x3e38aa3b, v66
	v_cndmask_b32_e32 v115, v248, v192, vcc
	v_cmp_lt_i32_e32 vcc, 31, v0
	v_fmamk_f32 v66, v67, 0x3e38aa3b, v160
	v_fmamk_f32 v67, v68, 0x3e38aa3b, v188
	v_cndmask_b32_e32 v116, v248, v82, vcc
	v_cmp_lt_i32_e32 vcc, 0, v0
	v_fmac_f32_e32 v189, 0x3e38aa3b, v69
	v_fmamk_f32 v68, v70, 0x3e38aa3b, v186
	v_cndmask_b32_e32 v117, v248, v66, vcc
	v_cmp_lt_i32_e32 vcc, 32, v0
	v_fmac_f32_e32 v187, 0x3e38aa3b, v71
	v_fmamk_f32 v69, v72, 0x3e38aa3b, v184
	v_cndmask_b32_e32 v118, v248, v83, vcc
	v_cmp_lt_i32_e32 vcc, 1, v0
	v_fmamk_f32 v89, v89, 0x3e38aa3b, v185
	v_fmac_f32_e32 v185, 0x3e38aa3b, v73
	v_cndmask_b32_e32 v119, v248, v67, vcc
	v_cmp_lt_i32_e32 vcc, 33, v0
	v_fmamk_f32 v70, v74, 0x3e38aa3b, v182
	v_fmamk_f32 v90, v90, 0x3e38aa3b, v182
	v_cndmask_b32_e32 v120, v248, v84, vcc
	v_cmp_lt_i32_e32 vcc, 2, v0
	v_fmamk_f32 v91, v91, 0x3e38aa3b, v183
	v_fmac_f32_e32 v183, 0x3e38aa3b, v75
	v_cndmask_b32_e32 v121, v248, v189, vcc
	v_cmp_lt_i32_e32 vcc, 34, v0
	v_fmamk_f32 v71, v76, 0x3e38aa3b, v180
	v_fmamk_f32 v92, v92, 0x3e38aa3b, v180
	v_cndmask_b32_e32 v122, v248, v85, vcc
	v_cmp_lt_i32_e32 vcc, 3, v0
	v_fmamk_f32 v93, v93, 0x3e38aa3b, v181
	v_fmac_f32_e32 v181, 0x3e38aa3b, v77
	v_cndmask_b32_e32 v123, v248, v68, vcc
	v_cmp_lt_i32_e32 vcc, 35, v0
	v_fmamk_f32 v72, v78, 0x3e38aa3b, v178
	v_fmamk_f32 v94, v94, 0x3e38aa3b, v178
	v_cndmask_b32_e32 v124, v248, v86, vcc
	v_cmp_lt_i32_e32 vcc, 4, v0
	v_fmamk_f32 v95, v95, 0x3e38aa3b, v179
	v_fmamk_f32 v96, v96, 0x3e38aa3b, v176
	v_cndmask_b32_e32 v125, v248, v187, vcc
	v_cmp_lt_i32_e32 vcc, 36, v0
	v_fmac_f32_e32 v179, 0x3e38aa3b, v79
	v_fmamk_f32 v73, v80, 0x3e38aa3b, v176
	v_cndmask_b32_e32 v127, v248, v87, vcc
	v_cmp_lt_i32_e32 vcc, 5, v0
	v_fmamk_f32 v97, v97, 0x3e38aa3b, v177
	v_fmac_f32_e32 v177, 0x3e38aa3b, v81
	v_cndmask_b32_e32 v128, v248, v69, vcc
	v_cmp_lt_i32_e32 vcc, 37, v0
	v_max3_f32 v66, v116, s54, v118
	v_max3_f32 v66, v66, v120, v122
	v_cndmask_b32_e32 v129, v248, v88, vcc
	v_cmp_lt_i32_e32 vcc, 6, v0
	v_max3_f32 v66, v66, v124, v127
	s_nop 0
	v_cndmask_b32_e32 v130, v248, v185, vcc
	v_cmp_lt_i32_e32 vcc, 38, v0
	s_nop 1
	v_cndmask_b32_e32 v131, v248, v89, vcc
	v_cmp_lt_i32_e32 vcc, 15, v0
	v_max3_f32 v66, v66, v129, v131
	s_nop 0
	v_cndmask_b32_e32 v137, v248, v70, vcc
	v_cmp_lt_i32_e32 vcc, 47, v0
	s_nop 1
	v_cndmask_b32_e32 v141, v248, v90, vcc
	v_cmp_lt_i32_e32 vcc, 16, v0
	s_nop 1
	v_cndmask_b32_e32 v145, v248, v183, vcc
	v_cmp_lt_i32_e32 vcc, 48, v0
	s_nop 1
	v_cndmask_b32_e32 v164, v248, v91, vcc
	v_cmp_lt_i32_e32 vcc, 17, v0
	v_max3_f32 v66, v66, v141, v164
	s_nop 0
	v_cndmask_b32_e32 v162, v248, v71, vcc
	v_cmp_lt_i32_e32 vcc, 49, v0
	s_nop 1
	v_cndmask_b32_e32 v165, v248, v92, vcc
	v_cmp_lt_i32_e32 vcc, 18, v0
	s_nop 1
	v_cndmask_b32_e32 v168, v248, v181, vcc
	v_cmp_lt_i32_e32 vcc, 50, v0
	s_nop 1
	v_cndmask_b32_e32 v170, v248, v93, vcc
	v_cmp_lt_i32_e32 vcc, 19, v0
	v_max3_f32 v66, v66, v165, v170
	s_nop 0
	v_cndmask_b32_e32 v171, v248, v72, vcc
	v_cmp_lt_i32_e32 vcc, 51, v0
	s_nop 1
	v_cndmask_b32_e32 v176, v248, v94, vcc
	v_cmp_lt_i32_e32 vcc, 20, v0
	s_nop 1
	v_cndmask_b32_e32 v178, v248, v179, vcc
	v_cmp_lt_i32_e32 vcc, 52, v0
	s_nop 1
	v_cndmask_b32_e32 v179, v248, v95, vcc
	v_cmp_lt_i32_e32 vcc, 21, v0
	v_max3_f32 v66, v66, v176, v179
	s_nop 0
	v_cndmask_b32_e32 v180, v248, v73, vcc
	v_cmp_lt_i32_e32 vcc, 53, v0
	s_nop 1
	v_cndmask_b32_e32 v181, v248, v96, vcc
	v_cmp_lt_i32_e32 vcc, 22, v0
	s_nop 1
	v_cndmask_b32_e32 v182, v248, v177, vcc
	v_cmp_lt_i32_e32 vcc, 54, v0
	v_max_f32_e32 v0, 0xff800000, v115
	v_max3_f32 v0, v0, v117, v119
	v_max3_f32 v0, v0, v121, v123
	v_max3_f32 v0, v0, v125, v128
	v_max3_f32 v0, v0, v130, v137
	v_cndmask_b32_e32 v183, v248, v97, vcc
	v_max3_f32 v0, v0, v145, v162
	v_max3_f32 v0, v0, v168, v171
	v_max3_f32 v66, v66, v181, v183
	v_max3_f32 v0, v0, v178, v180
	v_add_f32_e32 v66, v157, v66
	v_max3_f32 v0, v0, v182, v66
	v_fmac_f32_e32 v0, v160, v126
	v_mov_b32_e32 v66, v0
	s_nop 1
	v_permlane32_swap_b32_e32 v0, v66
	ds_read_b128 v[94:97], v212 offset:53248
	ds_read_b128 v[90:93], v212 offset:53280
	ds_read_b128 v[86:89], v212 offset:57856
	ds_read_b128 v[82:85], v212 offset:57888
	s_waitcnt lgkmcnt(4)
; DI float fexp2(float x) { return __builtin_amdgcn_exp2f(x); }
; DI void diff_attn_phase(int wv, LAS unsigned char* lds, const bf16_t* qk, const bf16_t* vt, bf16_t* ob, const float* lq1, const float* lk1, const float* lq2, const float* lk2,
;                         const float* subg, int layer_idx) {
;     ...
;                 {
;                     const float mn = fmaxf(m, mx), alpha = fexp2(m - mn); m = mn; l *= alpha;
; #pragma unroll
;                     for (int d = 0; d < 4; ++d) O[d] = O[d] * alpha;
;                 }
;                 const float off = base - m, off1 = off + b32;
;                 float ps = 0.f;
; #pragma unroll
;                 for (int i = 0; i < 16; ++i) { S0[i] = fexp2(S0[i] + off); S1[i] = fexp2(S1[i] + off1); ps += S0[i] + S1[i]; }
;                 l += ps;
;                 const bf16x8 p0 = pack8(S0, 0), p1 = pack8(S0, 1), p2 = pack8(S1, 0), p3 = pack8(S1, 1);
	v_max3_f32 v0, v218, v0, v66
	v_sub_f32_e32 v66, v218, v0
	v_exp_f32_e32 v114, v66
	v_fma_f32 v126, v160, v126, -v0
	v_add_f32_e32 v157, v157, v126
	v_add_f32_e32 v0, v115, v126
	v_pk_mul_f32 v[64:65], v[64:65], v[114:115] op_sel_hi:[1,0]
	v_pk_mul_f32 v[62:63], v[62:63], v[114:115] op_sel_hi:[1,0]
	v_pk_mul_f32 v[60:61], v[60:61], v[114:115] op_sel_hi:[1,0]
	v_pk_mul_f32 v[58:59], v[58:59], v[114:115] op_sel_hi:[1,0]
	v_pk_mul_f32 v[56:57], v[56:57], v[114:115] op_sel_hi:[1,0]
	v_pk_mul_f32 v[54:55], v[54:55], v[114:115] op_sel_hi:[1,0]
	v_pk_mul_f32 v[52:53], v[52:53], v[114:115] op_sel_hi:[1,0]
	v_pk_mul_f32 v[50:51], v[50:51], v[114:115] op_sel_hi:[1,0]
	v_pk_mul_f32 v[48:49], v[48:49], v[114:115] op_sel_hi:[1,0]
	v_pk_mul_f32 v[46:47], v[46:47], v[114:115] op_sel_hi:[1,0]
	v_pk_mul_f32 v[44:45], v[44:45], v[114:115] op_sel_hi:[1,0]
	v_pk_mul_f32 v[42:43], v[42:43], v[114:115] op_sel_hi:[1,0]
	v_pk_mul_f32 v[40:41], v[40:41], v[114:115] op_sel_hi:[1,0]
	v_pk_mul_f32 v[38:39], v[38:39], v[114:115] op_sel_hi:[1,0]
	v_pk_mul_f32 v[36:37], v[36:37], v[114:115] op_sel_hi:[1,0]
	v_pk_mul_f32 v[34:35], v[34:35], v[114:115] op_sel_hi:[1,0]
	v_pk_mul_f32 v[32:33], v[32:33], v[114:115] op_sel_hi:[1,0]
	v_pk_mul_f32 v[30:31], v[30:31], v[114:115] op_sel_hi:[1,0]
	v_pk_mul_f32 v[28:29], v[28:29], v[114:115] op_sel_hi:[1,0]
	v_pk_mul_f32 v[26:27], v[26:27], v[114:115] op_sel_hi:[1,0]
	v_pk_mul_f32 v[24:25], v[24:25], v[114:115] op_sel_hi:[1,0]
	v_pk_mul_f32 v[22:23], v[22:23], v[114:115] op_sel_hi:[1,0]
	v_pk_mul_f32 v[20:21], v[20:21], v[114:115] op_sel_hi:[1,0]
	v_pk_mul_f32 v[18:19], v[18:19], v[114:115] op_sel_hi:[1,0]
	v_pk_mul_f32 v[16:17], v[16:17], v[114:115] op_sel_hi:[1,0]
	v_pk_mul_f32 v[14:15], v[14:15], v[114:115] op_sel_hi:[1,0]
	v_pk_mul_f32 v[12:13], v[12:13], v[114:115] op_sel_hi:[1,0]
	v_pk_mul_f32 v[10:11], v[10:11], v[114:115] op_sel_hi:[1,0]
	v_pk_mul_f32 v[8:9], v[8:9], v[114:115] op_sel_hi:[1,0]
	v_exp_f32_e32 v115, v0
	v_add_f32_e32 v0, v116, v157
	v_add_f32_e32 v116, v119, v126
	v_exp_f32_e32 v160, v0
	v_add_f32_e32 v0, v117, v126
	v_exp_f32_e32 v117, v116
	v_add_f32_e32 v116, v120, v157
	v_exp_f32_e32 v184, v116
	v_add_f32_e32 v116, v121, v126
	v_exp_f32_e32 v134, v116
	v_add_f32_e32 v116, v122, v157
	v_exp_f32_e32 v136, v116
	v_add_f32_e32 v116, v125, v126
	v_exp_f32_e32 v138, v116
	v_add_f32_e32 v116, v127, v157
	v_exp_f32_e32 v140, v116
	v_add_f32_e32 v116, v130, v126
	v_exp_f32_e32 v142, v116
	v_add_f32_e32 v116, v131, v157
	v_add_f32_e32 v121, v141, v157
	v_exp_f32_e32 v144, v116
	v_add_f32_e32 v116, v145, v126
	v_add_f32_e32 v120, v129, v157
	v_exp_f32_e32 v129, v121
	v_add_f32_e32 v121, v162, v126
	v_exp_f32_e32 v162, v116
	v_add_f32_e32 v116, v164, v157
	v_exp_f32_e32 v164, v116
	v_add_f32_e32 v116, v168, v126
	v_exp_f32_e32 v168, v116
	v_add_f32_e32 v116, v170, v157
	v_exp_f32_e32 v170, v116
	v_add_f32_e32 v116, v178, v126
	ds_read_b128 v[78:81], v212 offset:62464
	ds_read_b128 v[74:77], v212 offset:62496
	ds_read_b128 v[70:73], v213 offset:13824
	ds_read_b128 v[66:69], v213 offset:13856
	v_exp_f32_e32 v132, v0
	v_add_f32_e32 v0, v118, v157
	v_add_f32_e32 v118, v123, v126
	v_add_f32_e32 v123, v176, v157
	v_exp_f32_e32 v176, v116
	v_add_f32_e32 v116, v179, v157
	v_add_f32_e32 v119, v124, v157
	v_add_f32_e32 v122, v165, v157
	v_exp_f32_e32 v178, v116
	v_add_f32_e32 v116, v182, v126
	v_exp_f32_e32 v185, v119
	v_add_f32_e32 v119, v128, v126
	v_exp_f32_e32 v128, v120
	v_add_f32_e32 v120, v137, v126
	v_exp_f32_e32 v130, v122
	v_add_f32_e32 v122, v171, v126
	v_exp_f32_e32 v131, v123
	v_add_f32_e32 v123, v180, v126
	v_add_f32_e32 v124, v181, v157
	v_exp_f32_e32 v180, v116
	v_add_f32_e32 v116, v183, v157
	v_exp_f32_e32 v0, v0
	v_exp_f32_e32 v118, v118
	v_exp_f32_e32 v119, v119
	v_exp_f32_e32 v120, v120
	v_exp_f32_e32 v121, v121
	v_exp_f32_e32 v122, v122
	v_exp_f32_e32 v123, v123
	v_exp_f32_e32 v137, v124
	v_exp_f32_e32 v182, v116
	v_pk_mul_f32 v[6:7], v[6:7], v[114:115] op_sel_hi:[1,0]
	v_pk_mul_f32 v[4:5], v[4:5], v[114:115] op_sel_hi:[1,0]
	v_pk_mul_f32 v[2:3], v[2:3], v[114:115] op_sel_hi:[1,0]
	v_add_f32_e32 v133, v115, v160
	v_add_f32_e32 v135, v117, v184
	v_add_f32_e32 v139, v118, v185
	v_add_f32_e32 v143, v119, v128
	v_add_f32_e32 v163, v120, v129
	v_add_f32_e32 v169, v121, v130
	v_add_f32_e32 v177, v122, v131
	v_add_f32_e32 v181, v123, v137
	v_cvt_pk_bf16_f32 v116, v115, v132
	v_cvt_pk_bf16_f32 v117, v117, v134
	v_cvt_pk_bf16_f32 v118, v118, v138
	v_cvt_pk_bf16_f32 v119, v119, v142
	v_cvt_pk_bf16_f32 v120, v120, v162
	v_cvt_pk_bf16_f32 v121, v121, v168
	v_cvt_pk_bf16_f32 v122, v122, v176
	v_cvt_pk_bf16_f32 v123, v123, v180
	v_cvt_pk_bf16_f32 v124, v160, v0
	v_cvt_pk_bf16_f32 v125, v184, v136
	v_cvt_pk_bf16_f32 v126, v185, v140
	v_cvt_pk_bf16_f32 v127, v128, v144
	v_cvt_pk_bf16_f32 v128, v129, v164
	v_cvt_pk_bf16_f32 v129, v130, v170
	v_cvt_pk_bf16_f32 v130, v131, v178
	v_cvt_pk_bf16_f32 v131, v137, v182
	s_waitcnt lgkmcnt(5)
; #define LAS __attribute__((address_space(3)))
; #define MFMA32(a, b, c) __builtin_amdgcn_mfma_f32_32x32x16_bf16((a), (b), (c), 0, 0, 0)
; DI void diff_attn_phase(int wv, LAS unsigned char* lds, const bf16_t* qk, const bf16_t* vt, bf16_t* ob, const float* lq1, const float* lk1, const float* lq2, const float* lk2,
;                         const float* subg, int layer_idx) {
;     ...
;                 l += ps;
;                 const bf16x8 p0 = pack8(S0, 0), p1 = pack8(S0, 1), p2 = pack8(S1, 0), p3 = pack8(S1, 1);
;                 __builtin_amdgcn_sched_barrier(0);
; #pragma unroll
;                 for (int d = 0; d < 4; ++d) { O[d] = MFMA32(vf[d][0], p0, O[d]); O[d] = MFMA32(vf[d][1], p1, O[d]); }
;                 __builtin_amdgcn_sched_barrier(0);
; #pragma unroll
;                 for (int d = 0; d < 4; ++d)
; #pragma unroll
;                     for (int s2 = 0; s2 < 2; ++s2) vf[d][s2] = *(const LAS bf16x8*)(buf + voff + d * 32 * DA_VP + (32 + 16 * s2) * 2);
; #pragma unroll
;                 for (int d = 0; d < 4; ++d) { O[d] = MFMA32(vf[d][0], p2, O[d]); O[d] = MFMA32(vf[d][1], p3, O[d]); }
	v_mfma_f32_32x32x16_bf16 v[34:49], v[86:89], v[116:119], v[34:49]
	s_waitcnt lgkmcnt(4)
	v_mfma_f32_32x32x16_bf16 v[34:49], v[82:85], v[120:123], v[34:49]
	v_add_f32_e64 v82, v132, v0
	v_add_f32_e64 v83, v133, v1
	s_waitcnt lgkmcnt(3)
	v_mfma_f32_32x32x16_bf16 v[18:33], v[78:81], v[116:119], v[18:33]
	v_add_f32_e64 v78, v82, v82
	v_add_f32_e64 v79, v82, v83
	v_mov_b32_e32 v137, v79
	v_add_f32_e64 v78, v134, v136
	v_add_f32_e64 v79, v135, v137
	v_pk_add_f32 v[78:79], v[78:79], v[78:79] op_sel_hi:[0,1]
	v_mov_b32_e32 v141, v79
	v_pk_add_f32 v[78:79], v[138:139], v[140:141]
	v_mfma_f32_32x32x16_bf16 v[50:65], v[94:97], v[116:119], v[50:65]
	v_pk_add_f32 v[78:79], v[78:79], v[78:79] op_sel_hi:[0,1]
	v_mov_b32_e32 v145, v79
	s_waitcnt lgkmcnt(1)
	v_mfma_f32_32x32x16_bf16 v[2:17], v[70:73], v[116:119], v[2:17]
	v_mfma_f32_32x32x16_bf16 v[18:33], v[74:77], v[120:123], v[18:33]
	v_add_f32_e64 v74, v142, v144
	v_add_f32_e64 v75, v143, v145
	v_pk_add_f32 v[74:75], v[74:75], v[74:75] op_sel_hi:[0,1]
	v_mov_b32_e32 v165, v75
	v_pk_add_f32 v[74:75], v[162:163], v[164:165]
	s_nop 0
	v_pk_add_f32 v[74:75], v[74:75], v[74:75] op_sel_hi:[0,1]
	v_mfma_f32_32x32x16_bf16 v[50:65], v[90:93], v[120:123], v[50:65]
	v_mov_b32_e32 v171, v75
	v_add_f32_e64 v70, v168, v170
	v_add_f32_e64 v71, v169, v171
	v_pk_add_f32 v[70:71], v[70:71], v[70:71] op_sel_hi:[0,1]
	v_mov_b32_e32 v179, v71
	v_pk_add_f32 v[70:71], v[176:177], v[178:179]
	s_waitcnt lgkmcnt(0)
	v_mfma_f32_32x32x16_bf16 v[2:17], v[66:69], v[120:123], v[2:17]
	v_pk_add_f32 v[70:71], v[70:71], v[70:71] op_sel_hi:[0,1]
	v_mov_b32_e32 v183, v71
	v_pk_add_f32 v[70:71], v[180:181], v[182:183]
	s_nop 0
	v_add_f32_e32 v0, v70, v71
	ds_read_b128 v[66:69], v212 offset:53312
	ds_read_b128 v[70:73], v212 offset:53344
	ds_read_b128 v[74:77], v212 offset:57920
	ds_read_b128 v[78:81], v212 offset:57952
	ds_read_b128 v[82:85], v212 offset:62528
	ds_read_b128 v[86:89], v212 offset:62560
	ds_read_b128 v[90:93], v213 offset:13888
	ds_read_b128 v[94:97], v213 offset:13920
	v_fmac_f32_e32 v0, v159, v114
	v_mov_b32_e32 v159, v0
	s_waitcnt lgkmcnt(7)
	v_mfma_f32_32x32x16_bf16 v[50:65], v[66:69], v[124:127], v[50:65]
	s_waitcnt lgkmcnt(6)
	v_mfma_f32_32x32x16_bf16 v[50:65], v[70:73], v[128:131], v[50:65]
	s_waitcnt lgkmcnt(5)
	v_mfma_f32_32x32x16_bf16 v[34:49], v[74:77], v[124:127], v[34:49]
	s_waitcnt lgkmcnt(4)
	v_mfma_f32_32x32x16_bf16 v[34:49], v[78:81], v[128:131], v[34:49]
	s_waitcnt lgkmcnt(3)
	v_mfma_f32_32x32x16_bf16 v[18:33], v[82:85], v[124:127], v[18:33]
	s_waitcnt lgkmcnt(2)
	v_mfma_f32_32x32x16_bf16 v[18:33], v[86:89], v[128:131], v[18:33]
	s_waitcnt lgkmcnt(1)
	v_mfma_f32_32x32x16_bf16 v[2:17], v[90:93], v[124:127], v[2:17]
	s_waitcnt lgkmcnt(0)
	v_mfma_f32_32x32x16_bf16 v[2:17], v[94:97], v[128:131], v[2:17]
